# code placement: GEMM K-loop heads (P1, P6, P8, P9) aligned to 64 bytes
# speedup vs baseline: 1.0151x; 1.0151x over previous
; DI void gemm_phase(LAS unsigned char* lds, const Gemm g, const StaticOrder& S, const Epi& E) {
;     ...
;         const char* nA = has_next ? (const char*)g.A + (size_t)nxt.pm * tsA : cA; const char* nB = has_next ? (const char*)g.Bt + (size_t)nxt.pn * tsB : cB;
;         for (int t = 0; t < nt; t += 2) {
;             const bool last = (t == nt - 2);
;             const char* a1 = cA + (size_t)(t + 1) * kstep;
;             const char* a2 = last ? nA : cA + (size_t)(t + 2) * kstep; const char* b2 = last ? nB : cB + (size_t)(t + 2) * kstep;
;             const char* a3 = a2 + kstep; const char* b3 = b2 + kstep;
;     ...
;         for (int a = 0; a < 2; ++a)
; #pragma unroll
;             for (int b = 0; b < 2; ++b)
; #pragma unroll
;                 for (int m = 0; m < 4; ++m)
; #pragma unroll
;                     for (int n = 0; n < 2; ++n) acc[a][b][m][n] = (f32x4){0.f, 0.f, 0.f, 0.f};
;         cur = nxt; cA = nA; cB = nB; ++ui;
.LBB0_176:
	s_ashr_i32 s23, s22, 31
	s_lshl_b64 s[24:25], s[22:23], 20
	s_add_u32 s24, s62, s24
	s_addc_u32 s25, s63, s25
	s_and_b64 s[26:27], s[2:3], exec
	s_cselect_b32 s5, s25, s31
	s_cselect_b32 s23, s24, s30
	s_ashr_i32 s21, s20, 31
	s_lshl_b64 s[26:27], s[20:21], 20
	s_add_u32 s26, s0, s26
	s_addc_u32 s27, s1, s27
	s_and_b64 s[38:39], s[2:3], exec
	s_cselect_b32 s21, s27, s35
	s_cselect_b32 s29, s26, s34
	s_add_u32 s30, s30, 0x80080
	s_addc_u32 s31, s31, 0
	s_add_u32 s54, s34, 0x100
	v_mov_b32_e32 v0, 0
	s_addc_u32 s55, s35, 0
	s_mov_b32 s56, -2
	v_mov_b64_e32 v[0:1], 0
	v_mov_b64_e32 v[2:3], 0
	v_mov_b64_e32 v[4:5], 0
	v_mov_b64_e32 v[6:7], 0
	v_mov_b64_e32 v[8:9], 0
	v_mov_b64_e32 v[10:11], 0
	v_mov_b64_e32 v[12:13], 0
	v_mov_b64_e32 v[14:15], 0
	v_mov_b64_e32 v[16:17], 0
	v_mov_b64_e32 v[18:19], 0
	v_mov_b64_e32 v[20:21], 0
	v_mov_b64_e32 v[22:23], 0
	v_mov_b64_e32 v[24:25], 0
	v_mov_b64_e32 v[26:27], 0
	v_mov_b64_e32 v[28:29], 0
	v_mov_b64_e32 v[30:31], 0
	v_mov_b64_e32 v[32:33], 0
	v_mov_b64_e32 v[34:35], 0
	v_mov_b64_e32 v[36:37], 0
	v_mov_b64_e32 v[38:39], 0
	v_mov_b64_e32 v[40:41], 0
	v_mov_b64_e32 v[42:43], 0
	v_mov_b64_e32 v[44:45], 0
	v_mov_b64_e32 v[46:47], 0
	v_mov_b64_e32 v[48:49], 0
	v_mov_b64_e32 v[50:51], 0
	v_mov_b64_e32 v[52:53], 0
	v_mov_b64_e32 v[54:55], 0
	v_mov_b64_e32 v[56:57], 0
	v_mov_b64_e32 v[58:59], 0
	v_mov_b64_e32 v[60:61], 0
	v_mov_b64_e32 v[62:63], 0
	v_mov_b64_e32 v[64:65], 0
	v_mov_b64_e32 v[66:67], 0
	v_mov_b64_e32 v[68:69], 0
	v_mov_b64_e32 v[70:71], 0
	v_mov_b64_e32 v[72:73], 0
	v_mov_b64_e32 v[74:75], 0
	v_mov_b64_e32 v[76:77], 0
	v_mov_b64_e32 v[78:79], 0
	v_mov_b64_e32 v[80:81], 0
	v_mov_b64_e32 v[82:83], 0
	v_mov_b64_e32 v[84:85], 0
	v_mov_b64_e32 v[86:87], 0
	v_mov_b64_e32 v[88:89], 0
	v_mov_b64_e32 v[90:91], 0
	v_mov_b64_e32 v[92:93], 0
	v_mov_b64_e32 v[94:95], 0
	v_mov_b64_e32 v[96:97], 0
	v_mov_b64_e32 v[98:99], 0
	v_mov_b64_e32 v[100:101], 0
	v_mov_b64_e32 v[102:103], 0
	v_mov_b64_e32 v[104:105], 0
	v_mov_b64_e32 v[106:107], 0
	v_mov_b64_e32 v[108:109], 0
	v_mov_b64_e32 v[110:111], 0
	v_mov_b64_e32 v[112:113], 0
	v_mov_b64_e32 v[114:115], 0
	v_mov_b64_e32 v[116:117], 0
	v_mov_b64_e32 v[118:119], 0
	v_mov_b64_e32 v[120:121], 0
	v_mov_b64_e32 v[122:123], 0
	v_mov_b64_e32 v[124:125], 0
	v_mov_b64_e32 v[126:127], 0
	s_cmp_eq_u32 s4, 10
	s_cselect_b64 vcc, -1, 0
	.p2align	6

; DI void gemm_phase(LAS unsigned char* lds, const Gemm g, const StaticOrder& S, const Epi& E) {
;     ...
;         const char* nA = has_next ? (const char*)g.A + (size_t)nxt.pm * tsA : cA; const char* nB = has_next ? (const char*)g.Bt + (size_t)nxt.pn * tsB : cB;
;         for (int t = 0; t < nt; t += 2) {
;             const bool last = (t == nt - 2);
;             const char* a1 = cA + (size_t)(t + 1) * kstep;
;             const char* a2 = last ? nA : cA + (size_t)(t + 2) * kstep; const char* b2 = last ? nB : cB + (size_t)(t + 2) * kstep;
;             const char* a3 = a2 + kstep; const char* b3 = b2 + kstep;
;     ...
;         for (int a = 0; a < 2; ++a)
; #pragma unroll
;             for (int b = 0; b < 2; ++b)
; #pragma unroll
;                 for (int m = 0; m < 4; ++m)
; #pragma unroll
;                     for (int n = 0; n < 2; ++n) acc[a][b][m][n] = (f32x4){0.f, 0.f, 0.f, 0.f};
;         cur = nxt; cA = nA; cB = nB; ++ui;
.LBB0_935:
	s_ashr_i32 s21, s20, 31
	s_lshl_b64 s[22:23], s[20:21], 20
	s_add_u32 s22, s53, s22
	s_addc_u32 s23, s54, s23
	s_and_b64 s[24:25], s[6:7], exec
	s_cselect_b32 s21, s23, s31
	s_cselect_b32 s27, s22, s30
	s_ashr_i32 s19, s18, 31
	s_lshl_b64 s[24:25], s[18:19], 20
	s_add_u32 s24, s0, s24
	s_addc_u32 s25, s1, s25
	s_and_b64 s[36:37], s[6:7], exec
	s_cselect_b32 s19, s25, s35
	s_cselect_b32 s48, s24, s34
	s_add_u32 s30, s30, 0x80080
	s_addc_u32 s31, s31, 0
	s_add_u32 s49, s34, 0x100
	v_mov_b32_e32 v0, 0
	s_addc_u32 s50, s35, 0
	s_mov_b32 s51, -2
	s_waitcnt lgkmcnt(0)
	v_mov_b64_e32 v[0:1], 0
	v_mov_b64_e32 v[2:3], 0
	v_mov_b64_e32 v[4:5], 0
	v_mov_b64_e32 v[6:7], 0
	v_mov_b64_e32 v[8:9], 0
	v_mov_b64_e32 v[10:11], 0
	v_mov_b64_e32 v[12:13], 0
	v_mov_b64_e32 v[14:15], 0
	v_mov_b64_e32 v[16:17], 0
	v_mov_b64_e32 v[18:19], 0
	v_mov_b64_e32 v[20:21], 0
	v_mov_b64_e32 v[22:23], 0
	v_mov_b64_e32 v[24:25], 0
	v_mov_b64_e32 v[26:27], 0
	v_mov_b64_e32 v[28:29], 0
	v_mov_b64_e32 v[30:31], 0
	v_mov_b64_e32 v[32:33], 0
	v_mov_b64_e32 v[34:35], 0
	v_mov_b64_e32 v[36:37], 0
	v_mov_b64_e32 v[38:39], 0
	v_mov_b64_e32 v[40:41], 0
	v_mov_b64_e32 v[42:43], 0
	v_mov_b64_e32 v[44:45], 0
	v_mov_b64_e32 v[46:47], 0
	v_mov_b64_e32 v[48:49], 0
	v_mov_b64_e32 v[50:51], 0
	v_mov_b64_e32 v[52:53], 0
	v_mov_b64_e32 v[54:55], 0
	v_mov_b64_e32 v[56:57], 0
	v_mov_b64_e32 v[58:59], 0
	v_mov_b64_e32 v[60:61], 0
	v_mov_b64_e32 v[62:63], 0
	v_mov_b64_e32 v[64:65], 0
	v_mov_b64_e32 v[66:67], 0
	v_mov_b64_e32 v[68:69], 0
	v_mov_b64_e32 v[70:71], 0
	v_mov_b64_e32 v[72:73], 0
	v_mov_b64_e32 v[74:75], 0
	v_mov_b64_e32 v[76:77], 0
	v_mov_b64_e32 v[78:79], 0
	v_mov_b64_e32 v[80:81], 0
	v_mov_b64_e32 v[82:83], 0
	v_mov_b64_e32 v[84:85], 0
	v_mov_b64_e32 v[86:87], 0
	v_mov_b64_e32 v[88:89], 0
	v_mov_b64_e32 v[90:91], 0
	v_mov_b64_e32 v[92:93], 0
	v_mov_b64_e32 v[94:95], 0
	v_mov_b64_e32 v[96:97], 0
	v_mov_b64_e32 v[98:99], 0
	v_mov_b64_e32 v[100:101], 0
	v_mov_b64_e32 v[102:103], 0
	v_mov_b64_e32 v[104:105], 0
	v_mov_b64_e32 v[106:107], 0
	v_mov_b64_e32 v[108:109], 0
	v_mov_b64_e32 v[110:111], 0
	v_mov_b64_e32 v[112:113], 0
	v_mov_b64_e32 v[114:115], 0
	v_mov_b64_e32 v[116:117], 0
	v_mov_b64_e32 v[118:119], 0
	v_mov_b64_e32 v[120:121], 0
	v_mov_b64_e32 v[122:123], 0
	v_mov_b64_e32 v[124:125], 0
	v_mov_b64_e32 v[126:127], 0
	.p2align	6

; DI void gemm_phase(LAS unsigned char* lds, const Gemm g, const StaticOrder& S, const Epi& E) {
;     ...
;         const char* nA = has_next ? (const char*)g.A + (size_t)nxt.pm * tsA : cA; const char* nB = has_next ? (const char*)g.Bt + (size_t)nxt.pn * tsB : cB;
;         for (int t = 0; t < nt; t += 2) {
;             const bool last = (t == nt - 2);
;             const char* a1 = cA + (size_t)(t + 1) * kstep;
;             const char* a2 = last ? nA : cA + (size_t)(t + 2) * kstep; const char* b2 = last ? nB : cB + (size_t)(t + 2) * kstep;
;             const char* a3 = a2 + kstep; const char* b3 = b2 + kstep;
;     ...
;         for (int a = 0; a < 2; ++a)
; #pragma unroll
;             for (int b = 0; b < 2; ++b)
; #pragma unroll
;                 for (int m = 0; m < 4; ++m)
; #pragma unroll
;                     for (int n = 0; n < 2; ++n) acc[a][b][m][n] = (f32x4){0.f, 0.f, 0.f, 0.f};
;         cur = nxt; cA = nA; cB = nB; ++ui;
.LBB0_1019:
	s_ashr_i32 s17, s16, 31
	s_lshl_b64 s[18:19], s[16:17], 20
	s_add_u32 s18, s62, s18
	s_addc_u32 s19, s63, s19
	s_and_b64 s[20:21], s[4:5], exec
	s_cselect_b32 s17, s19, s25
	s_cselect_b32 s41, s18, s24
	s_ashr_i32 s15, s14, 31
	s_lshl_b64 s[20:21], s[14:15], 20
	s_add_u32 s20, s0, s20
	s_addc_u32 s21, s1, s21
	s_and_b64 s[28:29], s[4:5], exec
	s_cselect_b32 s15, s21, s27
	s_cselect_b32 s42, s20, s26
	s_add_u32 s24, s24, 0x80080
	s_addc_u32 s25, s25, 0
	s_add_u32 s43, s26, 0x100
	v_mov_b32_e32 v0, 0
	s_addc_u32 s48, s27, 0
	s_mov_b32 s49, -2
	v_mov_b64_e32 v[0:1], 0
	v_mov_b64_e32 v[2:3], 0
	v_mov_b64_e32 v[4:5], 0
	v_mov_b64_e32 v[6:7], 0
	v_mov_b64_e32 v[8:9], 0
	v_mov_b64_e32 v[10:11], 0
	v_mov_b64_e32 v[12:13], 0
	v_mov_b64_e32 v[14:15], 0
	v_mov_b64_e32 v[16:17], 0
	v_mov_b64_e32 v[18:19], 0
	v_mov_b64_e32 v[20:21], 0
	v_mov_b64_e32 v[22:23], 0
	v_mov_b64_e32 v[24:25], 0
	v_mov_b64_e32 v[26:27], 0
	v_mov_b64_e32 v[28:29], 0
	v_mov_b64_e32 v[30:31], 0
	v_mov_b64_e32 v[32:33], 0
	v_mov_b64_e32 v[34:35], 0
	v_mov_b64_e32 v[36:37], 0
	v_mov_b64_e32 v[38:39], 0
	v_mov_b64_e32 v[40:41], 0
	v_mov_b64_e32 v[42:43], 0
	v_mov_b64_e32 v[44:45], 0
	v_mov_b64_e32 v[46:47], 0
	v_mov_b64_e32 v[48:49], 0
	v_mov_b64_e32 v[50:51], 0
	v_mov_b64_e32 v[52:53], 0
	v_mov_b64_e32 v[54:55], 0
	v_mov_b64_e32 v[56:57], 0
	v_mov_b64_e32 v[58:59], 0
	v_mov_b64_e32 v[60:61], 0
	v_mov_b64_e32 v[62:63], 0
	v_mov_b64_e32 v[64:65], 0
	v_mov_b64_e32 v[66:67], 0
	v_mov_b64_e32 v[68:69], 0
	v_mov_b64_e32 v[70:71], 0
	v_mov_b64_e32 v[72:73], 0
	v_mov_b64_e32 v[74:75], 0
	v_mov_b64_e32 v[76:77], 0
	v_mov_b64_e32 v[78:79], 0
	v_mov_b64_e32 v[80:81], 0
	v_mov_b64_e32 v[82:83], 0
	v_mov_b64_e32 v[84:85], 0
	v_mov_b64_e32 v[86:87], 0
	v_mov_b64_e32 v[88:89], 0
	v_mov_b64_e32 v[90:91], 0
	v_mov_b64_e32 v[92:93], 0
	v_mov_b64_e32 v[94:95], 0
	v_mov_b64_e32 v[96:97], 0
	v_mov_b64_e32 v[98:99], 0
	v_mov_b64_e32 v[100:101], 0
	v_mov_b64_e32 v[102:103], 0
	v_mov_b64_e32 v[104:105], 0
	v_mov_b64_e32 v[106:107], 0
	v_mov_b64_e32 v[108:109], 0
	v_mov_b64_e32 v[110:111], 0
	v_mov_b64_e32 v[112:113], 0
	v_mov_b64_e32 v[114:115], 0
	v_mov_b64_e32 v[116:117], 0
	v_mov_b64_e32 v[118:119], 0
	v_mov_b64_e32 v[120:121], 0
	v_mov_b64_e32 v[122:123], 0
	v_mov_b64_e32 v[124:125], 0
	v_mov_b64_e32 v[126:127], 0
	.p2align	6

; DI void gemm_phase(LAS unsigned char* lds, const Gemm g, const StaticOrder& S, const Epi& E) {
;     ...
;         const char* nA = has_next ? (const char*)g.A + (size_t)nxt.pm * tsA : cA; const char* nB = has_next ? (const char*)g.Bt + (size_t)nxt.pn * tsB : cB;
;         for (int t = 0; t < nt; t += 2) {
;             const bool last = (t == nt - 2);
;             const char* a1 = cA + (size_t)(t + 1) * kstep;
;             const char* a2 = last ? nA : cA + (size_t)(t + 2) * kstep; const char* b2 = last ? nB : cB + (size_t)(t + 2) * kstep;
;             const char* a3 = a2 + kstep; const char* b3 = b2 + kstep;
;     ...
;         for (int a = 0; a < 2; ++a)
; #pragma unroll
;             for (int b = 0; b < 2; ++b)
; #pragma unroll
;                 for (int m = 0; m < 4; ++m)
; #pragma unroll
;                     for (int n = 0; n < 2; ++n) acc[a][b][m][n] = (f32x4){0.f, 0.f, 0.f, 0.f};
;         cur = nxt; cA = nA; cB = nB; ++ui;
.LBB0_1100:
	s_add_u32 s51, s26, 0x100
	v_mov_b32_e32 v0, 0
	s_addc_u32 s52, s27, 0
	s_mov_b32 s53, -2
	v_mov_b64_e32 v[0:1], 0
	v_mov_b64_e32 v[2:3], 0
	v_mov_b64_e32 v[4:5], 0
	v_mov_b64_e32 v[6:7], 0
	v_mov_b64_e32 v[8:9], 0
	v_mov_b64_e32 v[10:11], 0
	v_mov_b64_e32 v[12:13], 0
	v_mov_b64_e32 v[14:15], 0
	v_mov_b64_e32 v[16:17], 0
	v_mov_b64_e32 v[18:19], 0
	v_mov_b64_e32 v[20:21], 0
	v_mov_b64_e32 v[22:23], 0
	v_mov_b64_e32 v[24:25], 0
	v_mov_b64_e32 v[26:27], 0
	v_mov_b64_e32 v[28:29], 0
	v_mov_b64_e32 v[30:31], 0
	v_mov_b64_e32 v[32:33], 0
	v_mov_b64_e32 v[34:35], 0
	v_mov_b64_e32 v[36:37], 0
	v_mov_b64_e32 v[38:39], 0
	v_mov_b64_e32 v[40:41], 0
	v_mov_b64_e32 v[42:43], 0
	v_mov_b64_e32 v[44:45], 0
	v_mov_b64_e32 v[46:47], 0
	v_mov_b64_e32 v[48:49], 0
	v_mov_b64_e32 v[50:51], 0
	v_mov_b64_e32 v[52:53], 0
	v_mov_b64_e32 v[54:55], 0
	v_mov_b64_e32 v[56:57], 0
	v_mov_b64_e32 v[58:59], 0
	v_mov_b64_e32 v[60:61], 0
	v_mov_b64_e32 v[62:63], 0
	v_mov_b64_e32 v[64:65], 0
	v_mov_b64_e32 v[66:67], 0
	v_mov_b64_e32 v[68:69], 0
	v_mov_b64_e32 v[70:71], 0
	v_mov_b64_e32 v[72:73], 0
	v_mov_b64_e32 v[74:75], 0
	v_mov_b64_e32 v[76:77], 0
	v_mov_b64_e32 v[78:79], 0
	v_mov_b64_e32 v[80:81], 0
	v_mov_b64_e32 v[82:83], 0
	v_mov_b64_e32 v[84:85], 0
	v_mov_b64_e32 v[86:87], 0
	v_mov_b64_e32 v[88:89], 0
	v_mov_b64_e32 v[90:91], 0
	v_mov_b64_e32 v[92:93], 0
	v_mov_b64_e32 v[94:95], 0
	v_mov_b64_e32 v[96:97], 0
	v_mov_b64_e32 v[98:99], 0
	v_mov_b64_e32 v[100:101], 0
	v_mov_b64_e32 v[102:103], 0
	v_mov_b64_e32 v[104:105], 0
	v_mov_b64_e32 v[106:107], 0
	v_mov_b64_e32 v[108:109], 0
	v_mov_b64_e32 v[110:111], 0
	v_mov_b64_e32 v[112:113], 0
	v_mov_b64_e32 v[114:115], 0
	v_mov_b64_e32 v[116:117], 0
	v_mov_b64_e32 v[118:119], 0
	v_mov_b64_e32 v[120:121], 0
	v_mov_b64_e32 v[122:123], 0
	v_mov_b64_e32 v[124:125], 0
	v_mov_b64_e32 v[126:127], 0
	.p2align	6
